# grid barrier: agent-scope L1 invalidate issued at arrival (workgroup parked, polls bypass L1) so it completes during the wait instead of after the release
# speedup vs baseline: 1.0759x; 1.0124x over previous
; DEV unsigned xb_ld(unsigned* p) { return __hip_atomic_load(p, __ATOMIC_RELAXED, __HIP_MEMORY_SCOPE_AGENT); }
; DEV unsigned xb_add(unsigned* p, unsigned v) { return __hip_atomic_fetch_add(p, v, __ATOMIC_RELAXED, __HIP_MEMORY_SCOPE_AGENT); }
; #define XB_SPIN(cond, bar) do { unsigned _sp = 0; while (cond) { __builtin_amdgcn_s_sleep(1); \
;     if ((++_sp & 255u) == 0u) { if (xb_ld(&(bar)[XB_TMO])) break; if (_sp > XB_SPIN_CAP) { atomicAdd(&(bar)[XB_TMO], 1u); break; } } } } while (0)
; DEV void xcd_barrier(const XcdBarrier& b) {
;     ...
;         const unsigned old = xb_add(&bar[XB_XSUB(b.x)], 1u);
;         const unsigned gen = old / nloc;
;         if (old + 1u == (gen + 1u) * nloc) {
;             __builtin_amdgcn_fence(__ATOMIC_RELEASE, "agent");
;             asm volatile("s_waitcnt vmcnt(0)" ::: "memory");
;             const unsigned og = xb_add(&bar[XB_TOP], 1u);
;             const unsigned tg = og / nx;
;             if (og + 1u == (tg + 1u) * nx) xb_add(&bar[XB_TOPGEN], 1u);
;             else XB_SPIN(xb_ld(&bar[XB_TOPGEN]) == tg, bar);
;             __builtin_amdgcn_fence(__ATOMIC_ACQUIRE, "agent");
;             xb_add(&bar[XB_XGEN(b.x)], 1u);
;             asm volatile("s_waitcnt vmcnt(0)" ::: "memory");
;         } else {
;             XB_SPIN(xb_ld(&bar[XB_XGEN(b.x)]) == gen, bar);
.LBB0_136:
	s_or_b64 exec, exec, s[10:11]
	v_cvt_f32_u32_e32 v5, v3
	s_waitcnt vmcnt(0)
	buffer_inv sc1
	v_readfirstlane_b32 s8, v4
	v_sub_u32_e32 v4, 0, v3
	v_rcp_iflag_f32_e32 v5, v5
	v_add_u32_e32 v6, s8, v2
	v_mul_f32_e32 v5, 0x4f7ffffe, v5
	v_cvt_u32_f32_e32 v5, v5
	v_mul_lo_u32 v2, v4, v5
	v_mul_hi_u32 v2, v5, v2
	v_add_u32_e32 v2, v5, v2
	v_mul_hi_u32 v2, v6, v2
	v_mul_lo_u32 v4, v2, v3
	v_sub_u32_e32 v4, v6, v4
	v_add_u32_e32 v5, 1, v2
	v_cmp_ge_u32_e32 vcc, v4, v3
	s_nop 1
	v_cndmask_b32_e32 v2, v2, v5, vcc
	v_sub_u32_e32 v5, v4, v3
	v_cndmask_b32_e32 v4, v4, v5, vcc
	v_add_u32_e32 v5, 1, v2
	v_cmp_ge_u32_e32 vcc, v4, v3
	v_add_u32_e32 v4, 1, v6
	s_nop 0
	v_cndmask_b32_e32 v2, v2, v5, vcc
	v_mul_lo_u32 v5, v3, v2
	v_add_u32_e32 v3, v5, v3
	v_cmp_ne_u32_e32 vcc, v4, v3
	s_and_saveexec_b64 s[8:9], vcc
	s_xor_b64 s[8:9], exec, s[8:9]
	s_cbranch_execz .LBB0_150
	s_waitcnt lgkmcnt(0)
	v_mov_b32_e32 v1, 0x2000
	global_load_dword v1, v1, s[6:7] offset:1024 sc1
	s_add_u32 s12, s6, 0x2400
	s_addc_u32 s13, s7, 0
	s_waitcnt vmcnt(0)
	v_cmp_eq_u32_e32 vcc, v1, v2
	s_and_saveexec_b64 s[10:11], vcc
	s_cbranch_execz .LBB0_149
	s_mov_b32 s26, 1
	s_mov_b64 s[16:17], 0
	v_mov_b32_e32 v1, 0
	s_branch .LBB0_140

; DEV unsigned xb_ld(unsigned* p) { return __hip_atomic_load(p, __ATOMIC_RELAXED, __HIP_MEMORY_SCOPE_AGENT); }
; #define XB_SPIN(cond, bar) do { unsigned _sp = 0; while (cond) { __builtin_amdgcn_s_sleep(1); \
;     if ((++_sp & 255u) == 0u) { if (xb_ld(&(bar)[XB_TMO])) break; if (_sp > XB_SPIN_CAP) { atomicAdd(&(bar)[XB_TMO], 1u); break; } } } } while (0)
; DEV void xcd_barrier(const XcdBarrier& b) {
;     ...
;             XB_SPIN(xb_ld(&bar[XB_XGEN(b.x)]) == gen, bar);
;             __builtin_amdgcn_fence(__ATOMIC_ACQUIRE, "agent");
;             asm volatile("s_waitcnt vmcnt(0)" ::: "memory");
.LBB0_149:
	s_or_b64 exec, exec, s[10:11]
	s_waitcnt vmcnt(0)

; DEV void xcd_barrier(const XcdBarrier& b) {
;     ...
;             asm volatile("s_waitcnt vmcnt(0)" ::: "memory");
	s_waitcnt vmcnt(0)

; DEV unsigned xb_add(unsigned* p, unsigned v) { return __hip_atomic_fetch_add(p, v, __ATOMIC_RELAXED, __HIP_MEMORY_SCOPE_AGENT); }
; DEV void xcd_barrier(const XcdBarrier& b) {
;     ...
;             __builtin_amdgcn_fence(__ATOMIC_ACQUIRE, "agent");
;             xb_add(&bar[XB_XGEN(b.x)], 1u);
.LBB0_167:
	s_or_b64 exec, exec, s[8:9]
	s_mov_b64 s[8:9], exec
	v_mbcnt_lo_u32_b32 v1, s8, 0
	v_mbcnt_hi_u32_b32 v1, s9, v1
	v_cmp_eq_u32_e32 vcc, 0, v1
	s_waitcnt vmcnt(0)

; DEV unsigned xb_add(unsigned* p, unsigned v) { return __hip_atomic_fetch_add(p, v, __ATOMIC_RELAXED, __HIP_MEMORY_SCOPE_AGENT); }
; DEV void xcd_barrier(const XcdBarrier& b) {
;     ...
;             xb_add(&bar[XB_XGEN(b.x)], 1u);
	s_and_saveexec_b64 s[10:11], vcc
	s_cbranch_execz .LBB0_169
	s_bcnt1_i32_b64 s8, s[8:9]
	v_mov_b32_e32 v1, 0x2000
	v_mov_b32_e32 v2, s8
	global_atomic_add v1, v2, s[6:7] offset:1024

; DEV unsigned xb_ld(unsigned* p) { return __hip_atomic_load(p, __ATOMIC_RELAXED, __HIP_MEMORY_SCOPE_AGENT); }
; DEV unsigned xb_add(unsigned* p, unsigned v) { return __hip_atomic_fetch_add(p, v, __ATOMIC_RELAXED, __HIP_MEMORY_SCOPE_AGENT); }
; #define XB_SPIN(cond, bar) do { unsigned _sp = 0; while (cond) { __builtin_amdgcn_s_sleep(1); \
;     if ((++_sp & 255u) == 0u) { if (xb_ld(&(bar)[XB_TMO])) break; if (_sp > XB_SPIN_CAP) { atomicAdd(&(bar)[XB_TMO], 1u); break; } } } } while (0)
; DEV void xcd_barrier(const XcdBarrier& b) {
;     ...
;         const unsigned old = xb_add(&bar[XB_XSUB(b.x)], 1u);
;         const unsigned gen = old / nloc;
;         if (old + 1u == (gen + 1u) * nloc) {
;             __builtin_amdgcn_fence(__ATOMIC_RELEASE, "agent");
;             asm volatile("s_waitcnt vmcnt(0)" ::: "memory");
;             const unsigned og = xb_add(&bar[XB_TOP], 1u);
;             const unsigned tg = og / nx;
;             if (og + 1u == (tg + 1u) * nx) xb_add(&bar[XB_TOPGEN], 1u);
;             else XB_SPIN(xb_ld(&bar[XB_TOPGEN]) == tg, bar);
;             __builtin_amdgcn_fence(__ATOMIC_ACQUIRE, "agent");
;             xb_add(&bar[XB_XGEN(b.x)], 1u);
;             asm volatile("s_waitcnt vmcnt(0)" ::: "memory");
;         } else {
;             XB_SPIN(xb_ld(&bar[XB_XGEN(b.x)]) == gen, bar);
.LBB0_1505:
	s_or_b64 exec, exec, s[10:11]
	v_cvt_f32_u32_e32 v5, v3
	s_waitcnt vmcnt(0)
	buffer_inv sc1
	v_readfirstlane_b32 s3, v4
	v_sub_u32_e32 v4, 0, v3
	v_rcp_iflag_f32_e32 v5, v5
	v_add_u32_e32 v6, s3, v2
	v_mul_f32_e32 v5, 0x4f7ffffe, v5
	v_cvt_u32_f32_e32 v5, v5
	v_mul_lo_u32 v2, v4, v5
	v_mul_hi_u32 v2, v5, v2
	v_add_u32_e32 v2, v5, v2
	v_mul_hi_u32 v2, v6, v2
	v_mul_lo_u32 v4, v2, v3
	v_sub_u32_e32 v4, v6, v4
	v_add_u32_e32 v5, 1, v2
	v_cmp_ge_u32_e32 vcc, v4, v3
	s_nop 1
	v_cndmask_b32_e32 v2, v2, v5, vcc
	v_sub_u32_e32 v5, v4, v3
	v_cndmask_b32_e32 v4, v4, v5, vcc
	v_add_u32_e32 v5, 1, v2
	v_cmp_ge_u32_e32 vcc, v4, v3
	v_add_u32_e32 v4, 1, v6
	s_nop 0
	v_cndmask_b32_e32 v2, v2, v5, vcc
	v_mul_lo_u32 v5, v3, v2
	v_add_u32_e32 v3, v5, v3
	v_cmp_ne_u32_e32 vcc, v4, v3
	s_and_saveexec_b64 s[8:9], vcc
	s_xor_b64 s[8:9], exec, s[8:9]
	s_cbranch_execz .LBB0_1519
	s_waitcnt lgkmcnt(0)
	v_mov_b32_e32 v1, 0x2000
	global_load_dword v1, v1, s[6:7] offset:1024 sc1
	s_add_u32 s12, s6, 0x2400
	s_addc_u32 s13, s7, 0
	s_waitcnt vmcnt(0)
	v_cmp_eq_u32_e32 vcc, v1, v2
	s_and_saveexec_b64 s[10:11], vcc
	s_cbranch_execz .LBB0_1518
	s_mov_b32 s3, 1
	s_mov_b64 s[14:15], 0
	v_mov_b32_e32 v1, 0
	s_branch .LBB0_1509

; DEV unsigned xb_add(unsigned* p, unsigned v) { return __hip_atomic_fetch_add(p, v, __ATOMIC_RELAXED, __HIP_MEMORY_SCOPE_AGENT); }
; DEV void xcd_barrier(const XcdBarrier& b) {
;     ...
;             __builtin_amdgcn_fence(__ATOMIC_ACQUIRE, "agent");
;             xb_add(&bar[XB_XGEN(b.x)], 1u);
.LBB0_1536:
	s_or_b64 exec, exec, s[8:9]
	s_mov_b64 s[8:9], exec
	v_mbcnt_lo_u32_b32 v1, s8, 0
	v_mbcnt_hi_u32_b32 v1, s9, v1
	v_cmp_eq_u32_e32 vcc, 0, v1
	s_waitcnt vmcnt(0)

; DEV unsigned xb_add(unsigned* p, unsigned v) { return __hip_atomic_fetch_add(p, v, __ATOMIC_RELAXED, __HIP_MEMORY_SCOPE_AGENT); }
; DEV void xcd_barrier(const XcdBarrier& b) {
;     ...
;             xb_add(&bar[XB_XGEN(b.x)], 1u);
	s_and_saveexec_b64 s[10:11], vcc
	s_cbranch_execz .LBB0_1538
	s_bcnt1_i32_b64 s3, s[8:9]
	v_mov_b32_e32 v1, 0x2000
	v_mov_b32_e32 v2, s3
	global_atomic_add v1, v2, s[6:7] offset:1024
